# fast loop: persistent DMA pointers + direct m0 writes, no-op lgkm waits removed, phase-B waits coarsened
# baseline (speedup 1.0000x reference)
; #define WAIT_BAR(N) asm volatile("s_waitcnt vmcnt(" #N ") lgkmcnt(0)\n\ts_barrier":::"memory")
;   #define RESC() do{ if(resc){ asm volatile("s_waitcnt lgkmcnt(0)":::"memory"); \
;       _Pragma("unroll") for(int d_=0;d_<2;++d_) _Pragma("unroll") for(int r=0;r<16;++r)o[d_][r]*=wsf[crow(r,hi)]; } }while(0)
;   #define ROT() do{sl_prev=sl_cur;sl_cur=sl_next;sl_next=(sl_next==(NSLOT-1)*SLOTB)?0:sl_next+SLOTB;}while(0)
;     ...
;   for(;t+5<NT;t+=2){
;     STEP(pB0,pB1,pA0,pA1,t,true,true,true);     WAIT_BAR(2); RESC(); ROT();
.Lfb_pre:
	v_lshl_add_u64 v[188:189], v[188:189], 0, s[20:21]
	v_lshl_add_u64 v[186:187], v[186:187], 0, s[20:21]
	s_mov_b64 s[0:1], 0x5d60e00
	v_lshl_add_u64 v[188:189], v[188:189], 0, s[0:1]
	s_mov_b64 s[0:1], 0x5cb1200
	v_lshl_add_u64 v[186:187], v[186:187], 0, s[0:1]
	v_mov_b32_e32 v192, 0x58000
	v_mov_b32_e32 v193, 0
	s_mov_b32 s0, 0
.Lfb_loop:
	v_add_u32_e32 v183, s0, v211
	ds_read_b64_tr_b16 v[178:179], v183 offset:24576
	ds_read_b64_tr_b16 v[180:181], v183 offset:25088
	v_mfma_f32_32x32x16_bf16 v[96:111], v[174:177], v[134:137], v[32:47]
	v_add_f32_e32 v80, v64, v65
	v_add_f32_e32 v80, v66, v80
	v_add_f32_e32 v80, v67, v80
	v_add_f32_e32 v80, v68, v80
	v_add_f32_e32 v80, v69, v80
	v_cvt_pk_bf16_f32 v142, v64, v65
	v_cvt_pk_bf16_f32 v143, v66, v67
	ds_read_b64_tr_b16 v[174:175], v183 offset:28672
	ds_read_b64_tr_b16 v[176:177], v183 offset:29184
	v_add_f32_e32 v64, v70, v80
	v_mfma_f32_32x32x16_bf16 v[80:95], v[170:173], v[134:137], v[32:47]
	v_add_f32_e32 v64, v71, v64
	v_add_f32_e32 v64, v72, v64
	v_add_f32_e32 v126, v73, v64
	v_cvt_pk_bf16_f32 v144, v68, v69
	v_cvt_pk_bf16_f32 v145, v70, v71
	ds_read_b64_tr_b16 v[64:65], v183 offset:25600
	ds_read_b64_tr_b16 v[66:67], v183 offset:26112
	v_mfma_f32_32x32x16_bf16 v[96:111], v[166:169], v[122:125], v[96:111]
	v_add_f32_e32 v68, v74, v126
	v_add_f32_e32 v68, v75, v68
	v_add_f32_e32 v68, v76, v68
	v_add_f32_e32 v126, v77, v68
	v_cvt_pk_bf16_f32 v138, v72, v73
	v_cvt_pk_bf16_f32 v139, v74, v75
	ds_read_b64_tr_b16 v[68:69], v183 offset:29696
	ds_read_b64_tr_b16 v[70:71], v183 offset:30208
	v_mfma_f32_32x32x16_bf16 v[80:95], v[162:165], v[122:125], v[80:95]
	v_add_f32_e32 v72, v78, v126
	v_add_f32_e32 v72, v79, v72
	v_add_f32_e32 v72, v48, v72
	v_add_f32_e32 v126, v49, v72
	v_cvt_pk_bf16_f32 v140, v76, v77
	v_cvt_pk_bf16_f32 v141, v78, v79
	ds_read_b64_tr_b16 v[72:73], v183 offset:26624
	ds_read_b64_tr_b16 v[74:75], v183 offset:27136
	v_mfma_f32_32x32x16_bf16 v[96:111], v[158:161], v[118:121], v[96:111]
	v_add_f32_e32 v76, v50, v126
	v_add_f32_e32 v76, v51, v76
	v_add_f32_e32 v76, v52, v76
	v_add_f32_e32 v76, v53, v76
	v_cvt_pk_bf16_f32 v130, v48, v49
	v_cvt_pk_bf16_f32 v131, v50, v51
	ds_read_b64_tr_b16 v[48:49], v183 offset:30720
	ds_read_b64_tr_b16 v[50:51], v183 offset:31232
	v_mfma_f32_32x32x16_bf16 v[80:95], v[154:157], v[118:121], v[80:95]
	v_add_f32_e32 v76, v54, v76
	v_add_f32_e32 v76, v55, v76
	v_add_f32_e32 v76, v56, v76
	v_add_f32_e32 v76, v57, v76
	v_cvt_pk_bf16_f32 v132, v52, v53
	v_cvt_pk_bf16_f32 v133, v54, v55
	ds_read_b64_tr_b16 v[52:53], v183 offset:27648
	ds_read_b64_tr_b16 v[54:55], v183 offset:28160
	v_mfma_f32_32x32x16_bf16 v[96:111], v[150:153], v[114:117], v[96:111]
	v_add_f32_e32 v76, v58, v76
	v_add_f32_e32 v76, v59, v76
	v_add_f32_e32 v76, v60, v76
	v_add_f32_e32 v76, v61, v76
	v_cvt_pk_bf16_f32 v126, v56, v57
	v_cvt_pk_bf16_f32 v127, v58, v59
	ds_read_b64_tr_b16 v[56:57], v183 offset:31744
	ds_read_b64_tr_b16 v[58:59], v183 offset:32256
	v_mfma_f32_32x32x16_bf16 v[80:95], v[146:149], v[114:117], v[80:95]
	v_add_f32_e32 v76, v62, v76
	v_add_f32_e32 v76, v63, v76
	v_cvt_pk_bf16_f32 v128, v60, v61
	v_cvt_pk_bf16_f32 v129, v62, v63
	s_add_i32 m0, s24, s69
	v_add_f32_e32 v185, v222, v76
	global_load_lds_dwordx4 v[188:189], off
	s_add_i32 m0, s13, s70
	v_lshl_add_u64 v[188:189], v[188:189], 0, v[192:193]
	global_load_lds_dwordx4 v[186:187], off
	v_lshl_add_u64 v[186:187], v[186:187], 0, v[192:193]
	s_waitcnt lgkmcnt(8)
	v_mfma_f32_32x32x16_bf16 v[16:31], v[142:145], v[178:181], v[16:31]
	v_exp_f32_e32 v96, v96
	v_exp_f32_e32 v97, v97
	v_exp_f32_e32 v98, v98
	v_exp_f32_e32 v99, v99
	v_mfma_f32_32x32x16_bf16 v[0:15], v[142:145], v[174:177], v[0:15]
	v_exp_f32_e32 v100, v100
	v_exp_f32_e32 v101, v101
	v_exp_f32_e32 v102, v102
	v_exp_f32_e32 v103, v103
	v_add_u32_e32 v76, s13, v210
	ds_read_b128 v[60:63], v76
	ds_read_b128 v[174:177], v76 offset:512
	v_mfma_f32_32x32x16_bf16 v[16:31], v[138:141], v[64:67], v[16:31]
	v_exp_f32_e32 v104, v104
	v_exp_f32_e32 v105, v105
	v_exp_f32_e32 v106, v106
	v_exp_f32_e32 v107, v107
	ds_read_b128 v[178:181], v76 offset:2048
	ds_read_b128 v[170:173], v76 offset:2560
	v_mfma_f32_32x32x16_bf16 v[0:15], v[138:141], v[68:71], v[0:15]
	v_exp_f32_e32 v108, v108
	v_exp_f32_e32 v109, v109
	v_exp_f32_e32 v110, v110
	v_exp_f32_e32 v111, v111
	ds_read_b128 v[166:169], v76 offset:4096
	ds_read_b128 v[162:165], v76 offset:4608
	s_waitcnt lgkmcnt(6)
	v_mfma_f32_32x32x16_bf16 v[16:31], v[130:133], v[72:75], v[16:31]
	v_exp_f32_e32 v80, v80
	v_exp_f32_e32 v81, v81
	v_exp_f32_e32 v82, v82
	v_exp_f32_e32 v83, v83
	ds_read_b128 v[158:161], v76 offset:6144
	ds_read_b128 v[154:157], v76 offset:6656
	v_mfma_f32_32x32x16_bf16 v[0:15], v[130:133], v[48:51], v[0:15]
	v_exp_f32_e32 v84, v84
	v_exp_f32_e32 v85, v85
	v_exp_f32_e32 v86, v86
	v_exp_f32_e32 v87, v87
	v_mfma_f32_32x32x16_bf16 v[16:31], v[126:129], v[52:55], v[16:31]
	v_exp_f32_e32 v88, v88
	v_exp_f32_e32 v89, v89
	v_exp_f32_e32 v90, v90
	v_exp_f32_e32 v91, v91
	v_mfma_f32_32x32x16_bf16 v[0:15], v[126:129], v[56:59], v[0:15]
	v_exp_f32_e32 v92, v92
	v_exp_f32_e32 v93, v93
	v_exp_f32_e32 v94, v94
	v_exp_f32_e32 v95, v95
	s_waitcnt vmcnt(2) lgkmcnt(0)
	s_barrier
; #define WAIT_BAR(N) asm volatile("s_waitcnt vmcnt(" #N ") lgkmcnt(0)\n\ts_barrier":::"memory")
;   #define RESC() do{ if(resc){ asm volatile("s_waitcnt lgkmcnt(0)":::"memory"); \
;       _Pragma("unroll") for(int d_=0;d_<2;++d_) _Pragma("unroll") for(int r=0;r<16;++r)o[d_][r]*=wsf[crow(r,hi)]; } }while(0)
;   #define ROT() do{sl_prev=sl_cur;sl_cur=sl_next;sl_next=(sl_next==(NSLOT-1)*SLOTB)?0:sl_next+SLOTB;}while(0)
;     ...
;     STEP(pB0,pB1,pA0,pA1,t,true,true,true);     WAIT_BAR(2); RESC(); ROT();
;     STEP(pA0,pA1,pB0,pB1,t+1,true,true,true);   WAIT_BAR(2); RESC(); ROT();
;   }
	s_add_i32 s0, s13, 0x2000
	s_cmpk_lg_i32 s13, 0x4000
	s_cselect_b32 s72, s0, 0
	v_add_u32_e32 v196, s24, v211
	ds_read_b64_tr_b16 v[150:151], v196 offset:24576
	ds_read_b64_tr_b16 v[152:153], v196 offset:25088
	v_mfma_f32_32x32x16_bf16 v[64:79], v[60:63], v[134:137], v[32:47]
	v_add_f32_e32 v48, v96, v97
	v_add_f32_e32 v48, v98, v48
	v_add_f32_e32 v48, v99, v48
	v_add_f32_e32 v48, v100, v48
	v_add_f32_e32 v48, v101, v48
	v_cvt_pk_bf16_f32 v142, v96, v97
	v_cvt_pk_bf16_f32 v143, v98, v99
	ds_read_b64_tr_b16 v[146:147], v196 offset:28672
	ds_read_b64_tr_b16 v[148:149], v196 offset:29184
	v_add_f32_e32 v48, v102, v48
	v_add_f32_e32 v48, v103, v48
	v_add_f32_e32 v48, v104, v48
	v_add_f32_e32 v126, v105, v48
	v_mfma_f32_32x32x16_bf16 v[48:63], v[174:177], v[134:137], v[32:47]
	v_cvt_pk_bf16_f32 v144, v100, v101
	v_cvt_pk_bf16_f32 v145, v102, v103
	ds_read_b64_tr_b16 v[96:97], v196 offset:25600
	ds_read_b64_tr_b16 v[98:99], v196 offset:26112
	v_mfma_f32_32x32x16_bf16 v[64:79], v[178:181], v[122:125], v[64:79]
	v_add_f32_e32 v100, v106, v126
	v_add_f32_e32 v100, v107, v100
	v_add_f32_e32 v100, v108, v100
	v_add_f32_e32 v126, v109, v100
	v_cvt_pk_bf16_f32 v138, v104, v105
	v_cvt_pk_bf16_f32 v139, v106, v107
	ds_read_b64_tr_b16 v[100:101], v196 offset:29696
	ds_read_b64_tr_b16 v[102:103], v196 offset:30208
	v_mfma_f32_32x32x16_bf16 v[48:63], v[170:173], v[122:125], v[48:63]
	v_add_f32_e32 v104, v110, v126
	v_add_f32_e32 v104, v111, v104
	v_add_f32_e32 v104, v80, v104
	v_add_f32_e32 v126, v81, v104
	v_cvt_pk_bf16_f32 v140, v108, v109
	v_cvt_pk_bf16_f32 v141, v110, v111
	ds_read_b64_tr_b16 v[104:105], v196 offset:26624
	ds_read_b64_tr_b16 v[106:107], v196 offset:27136
	v_mfma_f32_32x32x16_bf16 v[64:79], v[166:169], v[118:121], v[64:79]
	v_add_f32_e32 v108, v82, v126
	v_add_f32_e32 v108, v83, v108
	v_add_f32_e32 v108, v84, v108
	v_add_f32_e32 v108, v85, v108
	v_cvt_pk_bf16_f32 v130, v80, v81
	v_cvt_pk_bf16_f32 v131, v82, v83
	ds_read_b64_tr_b16 v[80:81], v196 offset:30720
	ds_read_b64_tr_b16 v[82:83], v196 offset:31232
	v_mfma_f32_32x32x16_bf16 v[48:63], v[162:165], v[118:121], v[48:63]
	v_add_f32_e32 v108, v86, v108
	v_add_f32_e32 v108, v87, v108
	v_add_f32_e32 v108, v88, v108
	v_add_f32_e32 v108, v89, v108
	v_cvt_pk_bf16_f32 v132, v84, v85
	v_cvt_pk_bf16_f32 v133, v86, v87
	ds_read_b64_tr_b16 v[84:85], v196 offset:27648
	ds_read_b64_tr_b16 v[86:87], v196 offset:28160
	v_mfma_f32_32x32x16_bf16 v[64:79], v[158:161], v[114:117], v[64:79]
	v_add_f32_e32 v108, v90, v108
	v_add_f32_e32 v108, v91, v108
	v_add_f32_e32 v108, v92, v108
	v_add_f32_e32 v108, v93, v108
	v_cvt_pk_bf16_f32 v126, v88, v89
	v_cvt_pk_bf16_f32 v127, v90, v91
	ds_read_b64_tr_b16 v[88:89], v196 offset:31744
	ds_read_b64_tr_b16 v[90:91], v196 offset:32256
	v_mfma_f32_32x32x16_bf16 v[48:63], v[154:157], v[114:117], v[48:63]
	v_add_f32_e32 v108, v94, v108
	v_add_f32_e32 v108, v95, v108
	v_cvt_pk_bf16_f32 v128, v92, v93
	v_cvt_pk_bf16_f32 v129, v94, v95
	s_add_i32 m0, s13, s69
	v_add_f32_e32 v222, v185, v108
	global_load_lds_dwordx4 v[188:189], off
	s_add_i32 m0, s72, s70
	v_lshl_add_u64 v[188:189], v[188:189], 0, v[192:193]
	global_load_lds_dwordx4 v[186:187], off
	v_lshl_add_u64 v[186:187], v[186:187], 0, v[192:193]
	s_waitcnt lgkmcnt(8)
	v_mfma_f32_32x32x16_bf16 v[16:31], v[142:145], v[150:153], v[16:31]
	v_exp_f32_e32 v64, v64
	v_exp_f32_e32 v65, v65
	v_exp_f32_e32 v66, v66
	v_exp_f32_e32 v67, v67
	v_mfma_f32_32x32x16_bf16 v[0:15], v[142:145], v[146:149], v[0:15]
	v_exp_f32_e32 v68, v68
	v_exp_f32_e32 v69, v69
	v_exp_f32_e32 v70, v70
	v_exp_f32_e32 v71, v71
	v_add_u32_e32 v92, s72, v210
	ds_read_b128 v[174:177], v92
	ds_read_b128 v[170:173], v92 offset:512
	v_mfma_f32_32x32x16_bf16 v[16:31], v[138:141], v[96:99], v[16:31]
	v_exp_f32_e32 v72, v72
	v_exp_f32_e32 v73, v73
	v_exp_f32_e32 v74, v74
	v_exp_f32_e32 v75, v75
	ds_read_b128 v[166:169], v92 offset:2048
	ds_read_b128 v[162:165], v92 offset:2560
	v_mfma_f32_32x32x16_bf16 v[0:15], v[138:141], v[100:103], v[0:15]
	v_exp_f32_e32 v76, v76
	v_exp_f32_e32 v77, v77
	v_exp_f32_e32 v78, v78
	v_exp_f32_e32 v79, v79
	ds_read_b128 v[158:161], v92 offset:4096
	ds_read_b128 v[154:157], v92 offset:4608
	s_waitcnt lgkmcnt(6)
	v_mfma_f32_32x32x16_bf16 v[16:31], v[130:133], v[104:107], v[16:31]
	v_exp_f32_e32 v48, v48
	v_exp_f32_e32 v49, v49
	v_exp_f32_e32 v50, v50
	v_exp_f32_e32 v51, v51
	ds_read_b128 v[150:153], v92 offset:6144
	ds_read_b128 v[146:149], v92 offset:6656
	v_mfma_f32_32x32x16_bf16 v[0:15], v[130:133], v[80:83], v[0:15]
	v_exp_f32_e32 v52, v52
	v_exp_f32_e32 v53, v53
	v_exp_f32_e32 v54, v54
	v_exp_f32_e32 v55, v55
	v_mfma_f32_32x32x16_bf16 v[16:31], v[126:129], v[84:87], v[16:31]
	v_exp_f32_e32 v56, v56
	v_exp_f32_e32 v57, v57
	v_exp_f32_e32 v58, v58
	v_exp_f32_e32 v59, v59
	v_mfma_f32_32x32x16_bf16 v[0:15], v[126:129], v[88:91], v[0:15]
	v_exp_f32_e32 v60, v60
	v_exp_f32_e32 v61, v61
	v_exp_f32_e32 v62, v62
	v_exp_f32_e32 v63, v63
	s_waitcnt vmcnt(2) lgkmcnt(0)
	s_barrier
	s_add_i32 s0, s72, 0x2000
	s_cmpk_lg_i32 s72, 0x4000
	s_cselect_b32 s74, s0, 0
	s_add_i32 s0, s75, 2
	s_cmp_ge_u32 s0, s71
	s_cbranch_scc1 .LBB0_1231
	s_mov_b32 s75, s0
	s_mov_b32 s0, s13
	s_mov_b32 s24, s72
	s_mov_b32 s13, s74
	s_branch .Lfb_loop
